# sample memory attention: pair B's gate load hoisted as well (both gate loads issued before pair-B's value loads)
# baseline (speedup 1.0000x reference)
.LBB0_590:
	s_or_b64 exec, exec, s[44:45]
	v_lshl_add_u64 v[32:33], v[136:137], 2, s[42:43]
	v_lshl_add_u64 v[32:33], v[32:33], 0, v[2:3]
	s_waitcnt lgkmcnt(3)
	v_add_co_u32_e32 v34, vcc, 0x1000, v32
	s_waitcnt lgkmcnt(2)
	s_nop 0
	v_addc_co_u32_e32 v35, vcc, 0, v33, vcc
	v_readlane_b32 s48, v254, 39
	v_readlane_b32 s49, v254, 40
	v_readlane_b32 s54, v255, 6
	v_readlane_b32 s55, v255, 7
	s_nop 1
	v_ashrrev_i32_e32 v151, 31, v132
	v_mov_b32_e32 v150, v132
	v_lshlrev_b64 v[150:151], 1, v[150:151]
	v_lshl_add_u64 v[154:155], s[54:55], 0, v[150:151]
	v_lshl_add_u64 v[156:157], s[48:49], 0, v[150:151]
	global_load_ushort v153, v[154:155], off
	global_load_ushort v152, v[156:157], off
	global_load_dwordx4 v[104:107], v[32:33], off nt
	global_load_dwordx4 v[100:103], v[34:35], off nt
	v_add_co_u32_e32 v34, vcc, 0x2000, v32
	s_nop 1
	v_addc_co_u32_e32 v35, vcc, 0, v33, vcc
	v_add_co_u32_e32 v44, vcc, 0x3000, v32
	s_nop 1
	v_addc_co_u32_e32 v45, vcc, 0, v33, vcc
	global_load_dwordx4 v[112:115], v[34:35], off nt
	global_load_dwordx4 v[108:111], v[44:45], off nt
	v_add_co_u32_e32 v34, vcc, s90, v32
	s_nop 1
	v_addc_co_u32_e32 v35, vcc, 0, v33, vcc
	v_add_co_u32_e32 v44, vcc, 0x5000, v32
	s_nop 1
	v_addc_co_u32_e32 v45, vcc, 0, v33, vcc
	global_load_dwordx4 v[120:123], v[34:35], off nt
	global_load_dwordx4 v[116:119], v[44:45], off nt
	v_add_co_u32_e32 v34, vcc, s33, v32
	s_nop 1
	v_addc_co_u32_e32 v35, vcc, 0, v33, vcc
	v_add_co_u32_e32 v44, vcc, 0x7000, v32
	s_nop 1
	v_addc_co_u32_e32 v45, vcc, 0, v33, vcc
	global_load_dwordx4 v[128:131], v[34:35], off nt
	global_load_dwordx4 v[124:127], v[44:45], off nt
	v_add_co_u32_e32 v34, vcc, s92, v32
	s_nop 1
	v_addc_co_u32_e32 v35, vcc, 0, v33, vcc
	v_add_co_u32_e32 v44, vcc, 0x9000, v32
	s_nop 1
	v_addc_co_u32_e32 v45, vcc, 0, v33, vcc
	global_load_dwordx4 v[96:99], v[34:35], off nt
	global_load_dwordx4 v[92:95], v[44:45], off nt
	v_add_co_u32_e32 v34, vcc, s93, v32
	s_nop 1
	v_addc_co_u32_e32 v35, vcc, 0, v33, vcc
	v_add_co_u32_e32 v44, vcc, 0xb000, v32
	s_nop 1
	v_addc_co_u32_e32 v45, vcc, 0, v33, vcc
	global_load_dwordx4 v[88:91], v[34:35], off nt
	global_load_dwordx4 v[84:87], v[44:45], off nt
	v_add_co_u32_e32 v34, vcc, s6, v32
	s_nop 1
	v_addc_co_u32_e32 v35, vcc, 0, v33, vcc
	v_add_co_u32_e32 v44, vcc, 0xd000, v32
	s_nop 1
	v_addc_co_u32_e32 v45, vcc, 0, v33, vcc
	global_load_dwordx4 v[64:67], v[34:35], off nt
	global_load_dwordx4 v[56:59], v[44:45], off nt
	v_add_co_u32_e32 v34, vcc, 0xe000, v32
	s_nop 1
	v_addc_co_u32_e32 v35, vcc, 0, v33, vcc
	v_add_co_u32_e32 v32, vcc, 0xf000, v32
	s_nop 1
	v_addc_co_u32_e32 v33, vcc, 0, v33, vcc
	s_waitcnt lgkmcnt(0)
	global_load_dwordx4 v[44:47], v[34:35], off nt
	s_nop 0
	global_load_dwordx4 v[32:35], v[32:33], off nt
	s_movk_i32 s1, 0x80
	v_cmp_gt_i32_e64 s[42:43], s1, v132
	v_ashrrev_i32_e32 v133, 31, v132
	v_lshl_add_u32 v2, v132, 2, 0
	s_barrier
	s_and_saveexec_b64 s[44:45], s[42:43]
	s_cbranch_execz .LBB0_592
	ds_read2st64_b32 v[136:137], v2 offset0:8 offset1:10
	v_readlane_b32 s46, v254, 39
	v_readlane_b32 s47, v254, 40
	s_waitcnt lgkmcnt(0)
	v_add_f32_e32 v136, 0, v136
	v_add_f32_e32 v147, v136, v137
	ds_read2st64_b32 v[136:137], v2 offset0:12 offset1:14
	s_waitcnt lgkmcnt(0)
	v_add_f32_e32 v136, v147, v136
	v_add_f32_e32 v147, v136, v137
	ds_read2st64_b32 v[136:137], v2 offset0:16 offset1:18
	s_waitcnt lgkmcnt(0)
	v_add_f32_e32 v136, v147, v136
	v_add_f32_e32 v147, v136, v137
	ds_read2st64_b32 v[136:137], v2 offset0:20 offset1:22
	s_waitcnt lgkmcnt(0)
	v_add_f32_e32 v136, v147, v136
	v_add_f32_e32 v147, v136, v137
	v_lshlrev_b64 v[136:137], 1, v[132:133]
	v_readlane_b32 s46, v255, 4
	v_readlane_b32 s47, v255, 5
	s_waitcnt vmcnt(16)
	v_lshlrev_b32_e32 v148, 16, v152
	v_mul_f32_e32 v147, v147, v148
	v_cvt_pk_bf16_f32 v147, v147, s0
	v_lshl_add_u64 v[136:137], s[46:47], 0, v[136:137]
	global_store_short v[136:137], v147, off sc1

.LBB0_626:
	s_or_b64 exec, exec, s[38:39]
	s_waitcnt lgkmcnt(0)
	s_barrier
	s_and_saveexec_b64 s[38:39], s[42:43]
	s_cbranch_execz .LBB0_538
	ds_read2st64_b32 v[4:5], v2 offset0:8 offset1:10
	v_readlane_b32 s40, v255, 6
	v_readlane_b32 s41, v255, 7
	s_waitcnt lgkmcnt(0)
	v_add_f32_e32 v4, 0, v4
	v_add_f32_e32 v6, v4, v5
	ds_read2st64_b32 v[4:5], v2 offset0:12 offset1:14
	s_waitcnt lgkmcnt(0)
	v_add_f32_e32 v4, v6, v4
	v_add_f32_e32 v6, v4, v5
	ds_read2st64_b32 v[4:5], v2 offset0:16 offset1:18
	s_waitcnt lgkmcnt(0)
	v_add_f32_e32 v4, v6, v4
	v_add_f32_e32 v6, v4, v5
	ds_read2st64_b32 v[4:5], v2 offset0:20 offset1:22
	s_waitcnt lgkmcnt(0)
	v_add_f32_e32 v2, v6, v4
	v_add_f32_e32 v2, v2, v5
	v_lshlrev_b64 v[4:5], 1, v[132:133]
	v_readlane_b32 s40, v255, 2
	v_readlane_b32 s41, v255, 3
	s_waitcnt vmcnt(0)
	v_lshlrev_b32_e32 v6, 16, v153
	v_mul_f32_e32 v2, v2, v6
	v_cvt_pk_bf16_f32 v2, v2, s0
	v_lshl_add_u64 v[4:5], s[40:41], 0, v[4:5]
	global_store_short v[4:5], v2, off sc1
	s_branch .LBB0_538

.LBB0_717:
	s_or_b64 exec, exec, s[44:45]
	v_lshl_add_u64 v[40:41], v[136:137], 2, s[46:47]
	v_lshl_add_u64 v[40:41], v[40:41], 0, v[2:3]
	s_waitcnt lgkmcnt(3)
	v_add_co_u32_e32 v42, vcc, 0x1000, v40
	s_waitcnt lgkmcnt(2)
	s_nop 0
	v_addc_co_u32_e32 v43, vcc, 0, v41, vcc
	v_ashrrev_i32_e32 v151, 31, v132
	v_mov_b32_e32 v150, v132
	v_lshlrev_b64 v[150:151], 1, v[150:151]
	v_lshl_add_u64 v[154:155], s[70:71], 0, v[150:151]
	v_lshl_add_u64 v[156:157], s[68:69], 0, v[150:151]
	global_load_ushort v153, v[154:155], off
	global_load_ushort v152, v[156:157], off
	global_load_dwordx4 v[104:107], v[40:41], off nt
	global_load_dwordx4 v[100:103], v[42:43], off nt
	v_add_co_u32_e32 v42, vcc, 0x2000, v40
	s_nop 1
	v_addc_co_u32_e32 v43, vcc, 0, v41, vcc
	v_add_co_u32_e32 v52, vcc, 0x3000, v40
	s_nop 1
	v_addc_co_u32_e32 v53, vcc, 0, v41, vcc
	global_load_dwordx4 v[112:115], v[42:43], off nt
	global_load_dwordx4 v[108:111], v[52:53], off nt
	v_add_co_u32_e32 v42, vcc, s14, v40
	s_nop 1
	v_addc_co_u32_e32 v43, vcc, 0, v41, vcc
	v_add_co_u32_e32 v52, vcc, 0x5000, v40
	s_nop 1
	v_addc_co_u32_e32 v53, vcc, 0, v41, vcc
	global_load_dwordx4 v[120:123], v[42:43], off nt
	global_load_dwordx4 v[116:119], v[52:53], off nt
	v_add_co_u32_e32 v42, vcc, s33, v40
	s_nop 1
	v_addc_co_u32_e32 v43, vcc, 0, v41, vcc
	v_add_co_u32_e32 v52, vcc, 0x7000, v40
	s_nop 1
	v_addc_co_u32_e32 v53, vcc, 0, v41, vcc
	global_load_dwordx4 v[128:131], v[42:43], off nt
	global_load_dwordx4 v[124:127], v[52:53], off nt
	v_add_co_u32_e32 v42, vcc, s24, v40
	s_nop 1
	v_addc_co_u32_e32 v43, vcc, 0, v41, vcc
	v_add_co_u32_e32 v52, vcc, 0x9000, v40
	s_nop 1
	v_addc_co_u32_e32 v53, vcc, 0, v41, vcc
	global_load_dwordx4 v[96:99], v[42:43], off nt
	global_load_dwordx4 v[92:95], v[52:53], off nt
	v_add_co_u32_e32 v42, vcc, s20, v40
	s_nop 1
	v_addc_co_u32_e32 v43, vcc, 0, v41, vcc
	v_add_co_u32_e32 v52, vcc, 0xb000, v40
	s_nop 1
	v_addc_co_u32_e32 v53, vcc, 0, v41, vcc
	global_load_dwordx4 v[88:91], v[42:43], off nt
	global_load_dwordx4 v[84:87], v[52:53], off nt
	v_add_co_u32_e32 v42, vcc, s6, v40
	s_nop 1
	v_addc_co_u32_e32 v43, vcc, 0, v41, vcc
	v_add_co_u32_e32 v52, vcc, 0xd000, v40
	s_nop 1
	v_addc_co_u32_e32 v53, vcc, 0, v41, vcc
	global_load_dwordx4 v[72:75], v[42:43], off nt
	global_load_dwordx4 v[64:67], v[52:53], off nt
	v_add_co_u32_e32 v42, vcc, 0xe000, v40
	s_nop 1
	v_addc_co_u32_e32 v43, vcc, 0, v41, vcc
	v_add_co_u32_e32 v40, vcc, 0xf000, v40
	s_nop 1
	v_addc_co_u32_e32 v41, vcc, 0, v41, vcc
	s_waitcnt lgkmcnt(0)
	global_load_dwordx4 v[52:55], v[42:43], off nt
	s_nop 0
	global_load_dwordx4 v[40:43], v[40:41], off nt
	s_movk_i32 s14, 0x80
	v_cmp_gt_i32_e64 s[44:45], s14, v132
	v_ashrrev_i32_e32 v133, 31, v132
	v_lshl_add_u32 v2, v132, 2, 0
	s_barrier
	s_and_saveexec_b64 s[46:47], s[44:45]
	s_cbranch_execz .LBB0_719
	ds_read2st64_b32 v[136:137], v2 offset0:8 offset1:10
	s_waitcnt lgkmcnt(0)
	v_add_f32_e32 v136, 0, v136
	v_add_f32_e32 v141, v136, v137
	ds_read2st64_b32 v[136:137], v2 offset0:12 offset1:14
	s_waitcnt lgkmcnt(0)
	v_add_f32_e32 v136, v141, v136
	v_add_f32_e32 v141, v136, v137
	ds_read2st64_b32 v[136:137], v2 offset0:16 offset1:18
	s_waitcnt lgkmcnt(0)
	v_add_f32_e32 v136, v141, v136
	v_add_f32_e32 v141, v136, v137
	ds_read2st64_b32 v[136:137], v2 offset0:20 offset1:22
	s_waitcnt lgkmcnt(0)
	v_add_f32_e32 v136, v141, v136
	v_add_f32_e32 v141, v136, v137
	v_lshlrev_b64 v[136:137], 1, v[132:133]
	v_lshl_add_u64 v[136:137], s[72:73], 0, v[136:137]
	s_waitcnt vmcnt(16)
	v_lshlrev_b32_e32 v142, 16, v152
	v_mul_f32_e32 v141, v141, v142
	v_cvt_pk_bf16_f32 v141, v141, s0
	global_store_short v[136:137], v141, off sc1

.LBB0_753:
	s_or_b64 exec, exec, s[40:41]
	s_waitcnt lgkmcnt(0)
	s_barrier
	s_and_saveexec_b64 s[40:41], s[44:45]
	s_cbranch_execz .LBB0_755
	ds_read2st64_b32 v[4:5], v2 offset0:8 offset1:10
	s_waitcnt lgkmcnt(0)
	v_add_f32_e32 v4, 0, v4
	v_add_f32_e32 v6, v4, v5
	ds_read2st64_b32 v[4:5], v2 offset0:12 offset1:14
	s_waitcnt lgkmcnt(0)
	v_add_f32_e32 v4, v6, v4
	v_add_f32_e32 v6, v4, v5
	ds_read2st64_b32 v[4:5], v2 offset0:16 offset1:18
	s_waitcnt lgkmcnt(0)
	v_add_f32_e32 v4, v6, v4
	v_add_f32_e32 v6, v4, v5
	ds_read2st64_b32 v[4:5], v2 offset0:20 offset1:22
	s_waitcnt lgkmcnt(0)
	v_add_f32_e32 v2, v6, v4
	v_add_f32_e32 v2, v2, v5
	v_lshlrev_b64 v[4:5], 1, v[132:133]
	v_lshl_add_u64 v[4:5], s[74:75], 0, v[4:5]
	s_waitcnt vmcnt(0)
	v_lshlrev_b32_e32 v6, 16, v153
	v_mul_f32_e32 v2, v2, v6
	v_cvt_pk_bf16_f32 v2, v2, s0
	global_store_short v[4:5], v2, off sc1
